# GEMM f32 epilogue modes 5/6: per-column bias vectors loaded once per unit instead of a load + full drain before each of the 32 stores
# speedup vs baseline: 1.0043x; 1.0043x over previous
; __device__ __forceinline__ void epilogue(const f32x4 (&acc)[2][2][4][2], const Unit& u, LAS unsigned char* lds, int wr, int wc, int fr, int fq) {
;     ...
;                     for (int n = 0; n < 2; ++n) { f32x4 v = acc[ai][bj][m][n];
;                         if (mode >= 5) { v += *(const f32x4*)(bias + col0 + bj * HALF + n * 16);
; #pragma unroll
;                             for (int q = 0; q < 4; ++q) { const float sg = __builtin_amdgcn_rcpf(1.f + __expf(-v[q])); v[q] = mode == 5 ? __expf(-0.6065306597126334f * sg) : sg; } }
;                         *(f32x4*)(rowp + bj * HALF + n * 16) = v; }
.LBB0_2468:
	v_pk_add_f32 v[122:123], v[122:123], v[246:247]
	v_pk_add_f32 v[120:121], v[120:121], v[244:245]
	v_mul_f32_e32 v122, 0xbfb8aa3b, v122
	v_mul_f32_e32 v120, 0xbfb8aa3b, v120
	v_mul_f32_e32 v121, 0xbfb8aa3b, v121
	v_mul_f32_e32 v123, 0xbfb8aa3b, v123
	v_exp_f32_e32 v120, v120
	v_exp_f32_e32 v121, v121
	v_exp_f32_e32 v122, v122
	v_exp_f32_e32 v123, v123
	v_add_f32_e32 v120, 1.0, v120
	v_add_f32_e32 v121, 1.0, v121
	v_add_f32_e32 v122, 1.0, v122
	v_add_f32_e32 v123, 1.0, v123
	v_rcp_f32_e32 v120, v120
	v_rcp_f32_e32 v121, v121
	v_rcp_f32_e32 v122, v122
	v_rcp_f32_e32 v123, v123
	v_mul_f32_e32 v124, 0xbf1b4598, v120
	v_mul_f32_e32 v125, 0xbf1b4598, v121
	v_mul_f32_e32 v126, 0xbf1b4598, v122
	v_mul_f32_e32 v127, 0xbf1b4598, v123
	v_mul_f32_e32 v124, 0x3fb8aa3b, v124
	v_mul_f32_e32 v125, 0x3fb8aa3b, v125
	v_mul_f32_e32 v126, 0x3fb8aa3b, v126
	v_mul_f32_e32 v127, 0x3fb8aa3b, v127
	v_exp_f32_e32 v124, v124
	v_exp_f32_e32 v125, v125
	v_exp_f32_e32 v126, v126
	v_exp_f32_e32 v127, v127
	v_cndmask_b32_e64 v120, v120, v124, s[8:9]
	v_cndmask_b32_e64 v121, v121, v125, s[8:9]
	v_cndmask_b32_e64 v122, v122, v126, s[8:9]
	v_cndmask_b32_e64 v123, v123, v127, s[8:9]
	flat_store_dwordx4 v[144:145], v[120:123] offset:512
	v_pk_add_f32 v[118:119], v[118:119], v[250:251]
	v_pk_add_f32 v[116:117], v[116:117], v[248:249]
	v_mul_f32_e32 v118, 0xbfb8aa3b, v118
	v_mul_f32_e32 v116, 0xbfb8aa3b, v116
	v_mul_f32_e32 v117, 0xbfb8aa3b, v117
	v_mul_f32_e32 v119, 0xbfb8aa3b, v119
	v_exp_f32_e32 v116, v116
	v_exp_f32_e32 v117, v117
	v_exp_f32_e32 v118, v118
	v_exp_f32_e32 v119, v119
	v_add_f32_e32 v116, 1.0, v116
	v_add_f32_e32 v117, 1.0, v117
	v_add_f32_e32 v118, 1.0, v118
	v_add_f32_e32 v119, 1.0, v119
	v_rcp_f32_e32 v116, v116
	v_rcp_f32_e32 v117, v117
	v_rcp_f32_e32 v118, v118
	v_rcp_f32_e32 v119, v119
	v_mul_f32_e32 v120, 0xbf1b4598, v116
	v_mul_f32_e32 v121, 0xbf1b4598, v117
	v_mul_f32_e32 v122, 0xbf1b4598, v118
	v_mul_f32_e32 v123, 0xbf1b4598, v119
	v_mul_f32_e32 v120, 0x3fb8aa3b, v120
	v_mul_f32_e32 v121, 0x3fb8aa3b, v121
	v_mul_f32_e32 v122, 0x3fb8aa3b, v122
	v_mul_f32_e32 v123, 0x3fb8aa3b, v123
	v_exp_f32_e32 v120, v120
	v_exp_f32_e32 v121, v121
	v_exp_f32_e32 v122, v122
	v_exp_f32_e32 v123, v123
	v_cndmask_b32_e64 v116, v116, v120, s[8:9]
	v_cndmask_b32_e64 v117, v117, v121, s[8:9]
	v_cndmask_b32_e64 v118, v118, v122, s[8:9]
	v_cndmask_b32_e64 v119, v119, v123, s[8:9]

; __device__ __forceinline__ void epilogue(const f32x4 (&acc)[2][2][4][2], const Unit& u, LAS unsigned char* lds, int wr, int wc, int fr, int fq) {
;     ...
;             for (int m = 0; m < 4; ++m) { float* rowp = C + (size_t)(row0 + ai * HALF + m * 16) * ldc + col0;
; #pragma unroll
;                 for (int bj = 0; bj < 2; ++bj)
; #pragma unroll
;                     for (int n = 0; n < 2; ++n) { f32x4 v = acc[ai][bj][m][n];
;                         if (mode >= 5) { v += *(const f32x4*)(bias + col0 + bj * HALF + n * 16);
; #pragma unroll
;                             for (int q = 0; q < 4; ++q) { const float sg = __builtin_amdgcn_rcpf(1.f + __expf(-v[q])); v[q] = mode == 5 ? __expf(-0.6065306597126334f * sg) : sg; } }
;                         *(f32x4*)(rowp + bj * HALF + n * 16) = v; }
;                 asm volatile("" ::: "memory"); }
.LBB0_2473:
	v_pk_add_f32 v[106:107], v[106:107], v[246:247]
	v_pk_add_f32 v[104:105], v[104:105], v[244:245]
	v_mul_f32_e32 v106, 0xbfb8aa3b, v106
	v_mul_f32_e32 v104, 0xbfb8aa3b, v104
	v_mul_f32_e32 v105, 0xbfb8aa3b, v105
	v_mul_f32_e32 v107, 0xbfb8aa3b, v107
	v_exp_f32_e32 v104, v104
	v_exp_f32_e32 v105, v105
	v_exp_f32_e32 v106, v106
	v_exp_f32_e32 v107, v107
	v_add_f32_e32 v104, 1.0, v104
	v_add_f32_e32 v105, 1.0, v105
	v_add_f32_e32 v106, 1.0, v106
	v_add_f32_e32 v107, 1.0, v107
	v_rcp_f32_e32 v104, v104
	v_rcp_f32_e32 v105, v105
	v_rcp_f32_e32 v106, v106
	v_rcp_f32_e32 v107, v107
	v_mul_f32_e32 v108, 0xbf1b4598, v104
	v_mul_f32_e32 v109, 0xbf1b4598, v105
	v_mul_f32_e32 v110, 0xbf1b4598, v106
	v_mul_f32_e32 v111, 0xbf1b4598, v107
	v_mul_f32_e32 v108, 0x3fb8aa3b, v108
	v_mul_f32_e32 v109, 0x3fb8aa3b, v109
	v_mul_f32_e32 v110, 0x3fb8aa3b, v110
	v_mul_f32_e32 v111, 0x3fb8aa3b, v111
	v_exp_f32_e32 v108, v108
	v_exp_f32_e32 v109, v109
	v_exp_f32_e32 v110, v110
	v_exp_f32_e32 v111, v111
	v_cndmask_b32_e64 v104, v104, v108, s[8:9]
	v_cndmask_b32_e64 v105, v105, v109, s[8:9]
	v_cndmask_b32_e64 v106, v106, v110, s[8:9]
	v_cndmask_b32_e64 v107, v107, v111, s[8:9]
	flat_store_dwordx4 v[116:117], v[104:107] offset:512
	v_pk_add_f32 v[102:103], v[102:103], v[250:251]
	v_pk_add_f32 v[100:101], v[100:101], v[248:249]
	v_mul_f32_e32 v102, 0xbfb8aa3b, v102
	v_mul_f32_e32 v100, 0xbfb8aa3b, v100
	v_mul_f32_e32 v101, 0xbfb8aa3b, v101
	v_mul_f32_e32 v103, 0xbfb8aa3b, v103
	v_exp_f32_e32 v100, v100
	v_exp_f32_e32 v101, v101
	v_exp_f32_e32 v102, v102
	v_exp_f32_e32 v103, v103
	v_add_f32_e32 v100, 1.0, v100
	v_add_f32_e32 v101, 1.0, v101
	v_add_f32_e32 v102, 1.0, v102
	v_add_f32_e32 v103, 1.0, v103
	v_rcp_f32_e32 v100, v100
	v_rcp_f32_e32 v101, v101
	v_rcp_f32_e32 v102, v102
	v_rcp_f32_e32 v103, v103
	v_mul_f32_e32 v104, 0xbf1b4598, v100
	v_mul_f32_e32 v105, 0xbf1b4598, v101
	v_mul_f32_e32 v106, 0xbf1b4598, v102
	v_mul_f32_e32 v107, 0xbf1b4598, v103
	v_mul_f32_e32 v104, 0x3fb8aa3b, v104
	v_mul_f32_e32 v105, 0x3fb8aa3b, v105
	v_mul_f32_e32 v106, 0x3fb8aa3b, v106
	v_mul_f32_e32 v107, 0x3fb8aa3b, v107
	v_exp_f32_e32 v104, v104
	v_exp_f32_e32 v105, v105
	v_exp_f32_e32 v106, v106
	v_exp_f32_e32 v107, v107
	v_cndmask_b32_e64 v100, v100, v104, s[8:9]
	v_cndmask_b32_e64 v101, v101, v105, s[8:9]
	v_cndmask_b32_e64 v102, v102, v106, s[8:9]
	v_cndmask_b32_e64 v103, v103, v107, s[8:9]

; __device__ __forceinline__ void epilogue(const f32x4 (&acc)[2][2][4][2], const Unit& u, LAS unsigned char* lds, int wr, int wc, int fr, int fq) {
;     ...
;             for (int m = 0; m < 4; ++m) { float* rowp = C + (size_t)(row0 + ai * HALF + m * 16) * ldc + col0;
; #pragma unroll
;                 for (int bj = 0; bj < 2; ++bj)
; #pragma unroll
;                     for (int n = 0; n < 2; ++n) { f32x4 v = acc[ai][bj][m][n];
;                         if (mode >= 5) { v += *(const f32x4*)(bias + col0 + bj * HALF + n * 16);
; #pragma unroll
;                             for (int q = 0; q < 4; ++q) { const float sg = __builtin_amdgcn_rcpf(1.f + __expf(-v[q])); v[q] = mode == 5 ? __expf(-0.6065306597126334f * sg) : sg; } }
;                         *(f32x4*)(rowp + bj * HALF + n * 16) = v; }
;                 asm volatile("" ::: "memory"); }
.LBB0_2478:
	v_pk_add_f32 v[90:91], v[90:91], v[246:247]
	v_pk_add_f32 v[88:89], v[88:89], v[244:245]
	v_mul_f32_e32 v90, 0xbfb8aa3b, v90
	v_mul_f32_e32 v88, 0xbfb8aa3b, v88
	v_mul_f32_e32 v89, 0xbfb8aa3b, v89
	v_mul_f32_e32 v91, 0xbfb8aa3b, v91
	v_exp_f32_e32 v88, v88
	v_exp_f32_e32 v89, v89
	v_exp_f32_e32 v90, v90
	v_exp_f32_e32 v91, v91
	v_add_f32_e32 v88, 1.0, v88
	v_add_f32_e32 v89, 1.0, v89
	v_add_f32_e32 v90, 1.0, v90
	v_add_f32_e32 v91, 1.0, v91
	v_rcp_f32_e32 v88, v88
	v_rcp_f32_e32 v89, v89
	v_rcp_f32_e32 v90, v90
	v_rcp_f32_e32 v91, v91
	v_mul_f32_e32 v92, 0xbf1b4598, v88
	v_mul_f32_e32 v93, 0xbf1b4598, v89
	v_mul_f32_e32 v94, 0xbf1b4598, v90
	v_mul_f32_e32 v95, 0xbf1b4598, v91
	v_mul_f32_e32 v92, 0x3fb8aa3b, v92
	v_mul_f32_e32 v93, 0x3fb8aa3b, v93
	v_mul_f32_e32 v94, 0x3fb8aa3b, v94
	v_mul_f32_e32 v95, 0x3fb8aa3b, v95
	v_exp_f32_e32 v92, v92
	v_exp_f32_e32 v93, v93
	v_exp_f32_e32 v94, v94
	v_exp_f32_e32 v95, v95
	v_cndmask_b32_e64 v88, v88, v92, s[8:9]
	v_cndmask_b32_e64 v89, v89, v93, s[8:9]
	v_cndmask_b32_e64 v90, v90, v94, s[8:9]
	v_cndmask_b32_e64 v91, v91, v95, s[8:9]
	flat_store_dwordx4 v[100:101], v[88:91] offset:512
	v_pk_add_f32 v[86:87], v[86:87], v[250:251]
	v_pk_add_f32 v[84:85], v[84:85], v[248:249]
	v_mul_f32_e32 v86, 0xbfb8aa3b, v86
	v_mul_f32_e32 v84, 0xbfb8aa3b, v84
	v_mul_f32_e32 v85, 0xbfb8aa3b, v85
	v_mul_f32_e32 v87, 0xbfb8aa3b, v87
	v_exp_f32_e32 v84, v84
	v_exp_f32_e32 v85, v85
	v_exp_f32_e32 v86, v86
	v_exp_f32_e32 v87, v87
	v_add_f32_e32 v84, 1.0, v84
	v_add_f32_e32 v85, 1.0, v85
	v_add_f32_e32 v86, 1.0, v86
	v_add_f32_e32 v87, 1.0, v87
	v_rcp_f32_e32 v84, v84
	v_rcp_f32_e32 v85, v85
	v_rcp_f32_e32 v86, v86
	v_rcp_f32_e32 v87, v87
	v_mul_f32_e32 v88, 0xbf1b4598, v84
	v_mul_f32_e32 v89, 0xbf1b4598, v85
	v_mul_f32_e32 v90, 0xbf1b4598, v86
	v_mul_f32_e32 v91, 0xbf1b4598, v87
	v_mul_f32_e32 v88, 0x3fb8aa3b, v88
	v_mul_f32_e32 v89, 0x3fb8aa3b, v89
	v_mul_f32_e32 v90, 0x3fb8aa3b, v90
	v_mul_f32_e32 v91, 0x3fb8aa3b, v91
	v_exp_f32_e32 v88, v88
	v_exp_f32_e32 v89, v89
	v_exp_f32_e32 v90, v90
	v_exp_f32_e32 v91, v91
	v_cndmask_b32_e64 v84, v84, v88, s[8:9]
	v_cndmask_b32_e64 v85, v85, v89, s[8:9]
	v_cndmask_b32_e64 v86, v86, v90, s[8:9]
	v_cndmask_b32_e64 v87, v87, v91, s[8:9]

; __device__ __forceinline__ void epilogue(const f32x4 (&acc)[2][2][4][2], const Unit& u, LAS unsigned char* lds, int wr, int wc, int fr, int fq) {
;     ...
;             for (int m = 0; m < 4; ++m) { float* rowp = C + (size_t)(row0 + ai * HALF + m * 16) * ldc + col0;
; #pragma unroll
;                 for (int bj = 0; bj < 2; ++bj)
; #pragma unroll
;                     for (int n = 0; n < 2; ++n) { f32x4 v = acc[ai][bj][m][n];
;                         if (mode >= 5) { v += *(const f32x4*)(bias + col0 + bj * HALF + n * 16);
; #pragma unroll
;                             for (int q = 0; q < 4; ++q) { const float sg = __builtin_amdgcn_rcpf(1.f + __expf(-v[q])); v[q] = mode == 5 ? __expf(-0.6065306597126334f * sg) : sg; } }
;                         *(f32x4*)(rowp + bj * HALF + n * 16) = v; }
;                 asm volatile("" ::: "memory"); }
.LBB0_2483:
	v_pk_add_f32 v[74:75], v[74:75], v[246:247]
	v_pk_add_f32 v[72:73], v[72:73], v[244:245]
	v_mul_f32_e32 v74, 0xbfb8aa3b, v74
	v_mul_f32_e32 v72, 0xbfb8aa3b, v72
	v_mul_f32_e32 v73, 0xbfb8aa3b, v73
	v_mul_f32_e32 v75, 0xbfb8aa3b, v75
	v_exp_f32_e32 v72, v72
	v_exp_f32_e32 v73, v73
	v_exp_f32_e32 v74, v74
	v_exp_f32_e32 v75, v75
	v_add_f32_e32 v72, 1.0, v72
	v_add_f32_e32 v73, 1.0, v73
	v_add_f32_e32 v74, 1.0, v74
	v_add_f32_e32 v75, 1.0, v75
	v_rcp_f32_e32 v72, v72
	v_rcp_f32_e32 v73, v73
	v_rcp_f32_e32 v74, v74
	v_rcp_f32_e32 v75, v75
	v_mul_f32_e32 v76, 0xbf1b4598, v72
	v_mul_f32_e32 v77, 0xbf1b4598, v73
	v_mul_f32_e32 v78, 0xbf1b4598, v74
	v_mul_f32_e32 v79, 0xbf1b4598, v75
	v_mul_f32_e32 v76, 0x3fb8aa3b, v76
	v_mul_f32_e32 v77, 0x3fb8aa3b, v77
	v_mul_f32_e32 v78, 0x3fb8aa3b, v78
	v_mul_f32_e32 v79, 0x3fb8aa3b, v79
	v_exp_f32_e32 v76, v76
	v_exp_f32_e32 v77, v77
	v_exp_f32_e32 v78, v78
	v_exp_f32_e32 v79, v79
	v_cndmask_b32_e64 v72, v72, v76, s[8:9]
	v_cndmask_b32_e64 v73, v73, v77, s[8:9]
	v_cndmask_b32_e64 v74, v74, v78, s[8:9]
	v_cndmask_b32_e64 v75, v75, v79, s[8:9]
	flat_store_dwordx4 v[84:85], v[72:75] offset:512
	v_pk_add_f32 v[70:71], v[70:71], v[250:251]
	v_pk_add_f32 v[68:69], v[68:69], v[248:249]
	v_mul_f32_e32 v70, 0xbfb8aa3b, v70
	v_mul_f32_e32 v68, 0xbfb8aa3b, v68
	v_mul_f32_e32 v69, 0xbfb8aa3b, v69
	v_mul_f32_e32 v71, 0xbfb8aa3b, v71
	v_exp_f32_e32 v68, v68
	v_exp_f32_e32 v69, v69
	v_exp_f32_e32 v70, v70
	v_exp_f32_e32 v71, v71
	v_add_f32_e32 v68, 1.0, v68
	v_add_f32_e32 v69, 1.0, v69
	v_add_f32_e32 v70, 1.0, v70
	v_add_f32_e32 v71, 1.0, v71
	v_rcp_f32_e32 v68, v68
	v_rcp_f32_e32 v69, v69
	v_rcp_f32_e32 v70, v70
	v_rcp_f32_e32 v71, v71
	v_mul_f32_e32 v72, 0xbf1b4598, v68
	v_mul_f32_e32 v73, 0xbf1b4598, v69
	v_mul_f32_e32 v74, 0xbf1b4598, v70
	v_mul_f32_e32 v75, 0xbf1b4598, v71
	v_mul_f32_e32 v72, 0x3fb8aa3b, v72
	v_mul_f32_e32 v73, 0x3fb8aa3b, v73
	v_mul_f32_e32 v74, 0x3fb8aa3b, v74
	v_mul_f32_e32 v75, 0x3fb8aa3b, v75
	v_exp_f32_e32 v72, v72
	v_exp_f32_e32 v73, v73
	v_exp_f32_e32 v74, v74
	v_exp_f32_e32 v75, v75
	v_cndmask_b32_e64 v68, v68, v72, s[8:9]
	v_cndmask_b32_e64 v69, v69, v73, s[8:9]
	v_cndmask_b32_e64 v70, v70, v74, s[8:9]
	v_cndmask_b32_e64 v71, v71, v75, s[8:9]

; __device__ __forceinline__ void epilogue(const f32x4 (&acc)[2][2][4][2], const Unit& u, LAS unsigned char* lds, int wr, int wc, int fr, int fq) {
;     ...
;             for (int m = 0; m < 4; ++m) { float* rowp = C + (size_t)(row0 + ai * HALF + m * 16) * ldc + col0;
; #pragma unroll
;                 for (int bj = 0; bj < 2; ++bj)
; #pragma unroll
;                     for (int n = 0; n < 2; ++n) { f32x4 v = acc[ai][bj][m][n];
;                         if (mode >= 5) { v += *(const f32x4*)(bias + col0 + bj * HALF + n * 16);
; #pragma unroll
;                             for (int q = 0; q < 4; ++q) { const float sg = __builtin_amdgcn_rcpf(1.f + __expf(-v[q])); v[q] = mode == 5 ? __expf(-0.6065306597126334f * sg) : sg; } }
;                         *(f32x4*)(rowp + bj * HALF + n * 16) = v; }
;                 asm volatile("" ::: "memory"); }
.LBB0_2488:
	v_pk_add_f32 v[58:59], v[58:59], v[246:247]
	v_pk_add_f32 v[56:57], v[56:57], v[244:245]
	v_mul_f32_e32 v58, 0xbfb8aa3b, v58
	v_mul_f32_e32 v56, 0xbfb8aa3b, v56
	v_mul_f32_e32 v57, 0xbfb8aa3b, v57
	v_mul_f32_e32 v59, 0xbfb8aa3b, v59
	v_exp_f32_e32 v56, v56
	v_exp_f32_e32 v57, v57
	v_exp_f32_e32 v58, v58
	v_exp_f32_e32 v59, v59
	v_add_f32_e32 v56, 1.0, v56
	v_add_f32_e32 v57, 1.0, v57
	v_add_f32_e32 v58, 1.0, v58
	v_add_f32_e32 v59, 1.0, v59
	v_rcp_f32_e32 v56, v56
	v_rcp_f32_e32 v57, v57
	v_rcp_f32_e32 v58, v58
	v_rcp_f32_e32 v59, v59
	v_mul_f32_e32 v60, 0xbf1b4598, v56
	v_mul_f32_e32 v61, 0xbf1b4598, v57
	v_mul_f32_e32 v62, 0xbf1b4598, v58
	v_mul_f32_e32 v63, 0xbf1b4598, v59
	v_mul_f32_e32 v60, 0x3fb8aa3b, v60
	v_mul_f32_e32 v61, 0x3fb8aa3b, v61
	v_mul_f32_e32 v62, 0x3fb8aa3b, v62
	v_mul_f32_e32 v63, 0x3fb8aa3b, v63
	v_exp_f32_e32 v60, v60
	v_exp_f32_e32 v61, v61
	v_exp_f32_e32 v62, v62
	v_exp_f32_e32 v63, v63
	v_cndmask_b32_e64 v56, v56, v60, s[8:9]
	v_cndmask_b32_e64 v57, v57, v61, s[8:9]
	v_cndmask_b32_e64 v58, v58, v62, s[8:9]
	v_cndmask_b32_e64 v59, v59, v63, s[8:9]
	flat_store_dwordx4 v[68:69], v[56:59] offset:512
	v_pk_add_f32 v[54:55], v[54:55], v[250:251]
	v_pk_add_f32 v[52:53], v[52:53], v[248:249]
	v_mul_f32_e32 v54, 0xbfb8aa3b, v54
	v_mul_f32_e32 v52, 0xbfb8aa3b, v52
	v_mul_f32_e32 v53, 0xbfb8aa3b, v53
	v_mul_f32_e32 v55, 0xbfb8aa3b, v55
	v_exp_f32_e32 v52, v52
	v_exp_f32_e32 v53, v53
	v_exp_f32_e32 v54, v54
	v_exp_f32_e32 v55, v55
	v_add_f32_e32 v52, 1.0, v52
	v_add_f32_e32 v53, 1.0, v53
	v_add_f32_e32 v54, 1.0, v54
	v_add_f32_e32 v55, 1.0, v55
	v_rcp_f32_e32 v52, v52
	v_rcp_f32_e32 v53, v53
	v_rcp_f32_e32 v54, v54
	v_rcp_f32_e32 v55, v55
	v_mul_f32_e32 v56, 0xbf1b4598, v52
	v_mul_f32_e32 v57, 0xbf1b4598, v53
	v_mul_f32_e32 v58, 0xbf1b4598, v54
	v_mul_f32_e32 v59, 0xbf1b4598, v55
	v_mul_f32_e32 v56, 0x3fb8aa3b, v56
	v_mul_f32_e32 v57, 0x3fb8aa3b, v57
	v_mul_f32_e32 v58, 0x3fb8aa3b, v58
	v_mul_f32_e32 v59, 0x3fb8aa3b, v59
	v_exp_f32_e32 v56, v56
	v_exp_f32_e32 v57, v57
	v_exp_f32_e32 v58, v58
	v_exp_f32_e32 v59, v59
	v_cndmask_b32_e64 v52, v52, v56, s[8:9]
	v_cndmask_b32_e64 v53, v53, v57, s[8:9]
	v_cndmask_b32_e64 v54, v54, v58, s[8:9]
	v_cndmask_b32_e64 v55, v55, v59, s[8:9]

; __device__ __forceinline__ void epilogue(const f32x4 (&acc)[2][2][4][2], const Unit& u, LAS unsigned char* lds, int wr, int wc, int fr, int fq) {
;     ...
;             for (int m = 0; m < 4; ++m) { float* rowp = C + (size_t)(row0 + ai * HALF + m * 16) * ldc + col0;
; #pragma unroll
;                 for (int bj = 0; bj < 2; ++bj)
; #pragma unroll
;                     for (int n = 0; n < 2; ++n) { f32x4 v = acc[ai][bj][m][n];
;                         if (mode >= 5) { v += *(const f32x4*)(bias + col0 + bj * HALF + n * 16);
; #pragma unroll
;                             for (int q = 0; q < 4; ++q) { const float sg = __builtin_amdgcn_rcpf(1.f + __expf(-v[q])); v[q] = mode == 5 ? __expf(-0.6065306597126334f * sg) : sg; } }
;                         *(f32x4*)(rowp + bj * HALF + n * 16) = v; }
;                 asm volatile("" ::: "memory"); }
.LBB0_2493:
	v_pk_add_f32 v[42:43], v[42:43], v[246:247]
	v_pk_add_f32 v[40:41], v[40:41], v[244:245]
	v_mul_f32_e32 v42, 0xbfb8aa3b, v42
	v_mul_f32_e32 v40, 0xbfb8aa3b, v40
	v_mul_f32_e32 v41, 0xbfb8aa3b, v41
	v_mul_f32_e32 v43, 0xbfb8aa3b, v43
	v_exp_f32_e32 v40, v40
	v_exp_f32_e32 v41, v41
	v_exp_f32_e32 v42, v42
	v_exp_f32_e32 v43, v43
	v_add_f32_e32 v40, 1.0, v40
	v_add_f32_e32 v41, 1.0, v41
	v_add_f32_e32 v42, 1.0, v42
	v_add_f32_e32 v43, 1.0, v43
	v_rcp_f32_e32 v40, v40
	v_rcp_f32_e32 v41, v41
	v_rcp_f32_e32 v42, v42
	v_rcp_f32_e32 v43, v43
	v_mul_f32_e32 v44, 0xbf1b4598, v40
	v_mul_f32_e32 v45, 0xbf1b4598, v41
	v_mul_f32_e32 v46, 0xbf1b4598, v42
	v_mul_f32_e32 v47, 0xbf1b4598, v43
	v_mul_f32_e32 v44, 0x3fb8aa3b, v44
	v_mul_f32_e32 v45, 0x3fb8aa3b, v45
	v_mul_f32_e32 v46, 0x3fb8aa3b, v46
	v_mul_f32_e32 v47, 0x3fb8aa3b, v47
	v_exp_f32_e32 v44, v44
	v_exp_f32_e32 v45, v45
	v_exp_f32_e32 v46, v46
	v_exp_f32_e32 v47, v47
	v_cndmask_b32_e64 v40, v40, v44, s[8:9]
	v_cndmask_b32_e64 v41, v41, v45, s[8:9]
	v_cndmask_b32_e64 v42, v42, v46, s[8:9]
	v_cndmask_b32_e64 v43, v43, v47, s[8:9]
	flat_store_dwordx4 v[52:53], v[40:43] offset:512
	v_pk_add_f32 v[38:39], v[38:39], v[250:251]
	v_pk_add_f32 v[36:37], v[36:37], v[248:249]
	v_mul_f32_e32 v38, 0xbfb8aa3b, v38
	v_mul_f32_e32 v36, 0xbfb8aa3b, v36
	v_mul_f32_e32 v37, 0xbfb8aa3b, v37
	v_mul_f32_e32 v39, 0xbfb8aa3b, v39
	v_exp_f32_e32 v36, v36
	v_exp_f32_e32 v37, v37
	v_exp_f32_e32 v38, v38
	v_exp_f32_e32 v39, v39
	v_add_f32_e32 v36, 1.0, v36
	v_add_f32_e32 v37, 1.0, v37
	v_add_f32_e32 v38, 1.0, v38
	v_add_f32_e32 v39, 1.0, v39
	v_rcp_f32_e32 v36, v36
	v_rcp_f32_e32 v37, v37
	v_rcp_f32_e32 v38, v38
	v_rcp_f32_e32 v39, v39
	v_mul_f32_e32 v40, 0xbf1b4598, v36
	v_mul_f32_e32 v41, 0xbf1b4598, v37
	v_mul_f32_e32 v42, 0xbf1b4598, v38
	v_mul_f32_e32 v43, 0xbf1b4598, v39
	v_mul_f32_e32 v40, 0x3fb8aa3b, v40
	v_mul_f32_e32 v41, 0x3fb8aa3b, v41
	v_mul_f32_e32 v42, 0x3fb8aa3b, v42
	v_mul_f32_e32 v43, 0x3fb8aa3b, v43
	v_exp_f32_e32 v40, v40
	v_exp_f32_e32 v41, v41
	v_exp_f32_e32 v42, v42
	v_exp_f32_e32 v43, v43
	v_cndmask_b32_e64 v36, v36, v40, s[8:9]
	v_cndmask_b32_e64 v37, v37, v41, s[8:9]
	v_cndmask_b32_e64 v38, v38, v42, s[8:9]
	v_cndmask_b32_e64 v39, v39, v43, s[8:9]

; __device__ __forceinline__ void epilogue(const f32x4 (&acc)[2][2][4][2], const Unit& u, LAS unsigned char* lds, int wr, int wc, int fr, int fq) {
;     ...
;             for (int m = 0; m < 4; ++m) { float* rowp = C + (size_t)(row0 + ai * HALF + m * 16) * ldc + col0;
; #pragma unroll
;                 for (int bj = 0; bj < 2; ++bj)
; #pragma unroll
;                     for (int n = 0; n < 2; ++n) { f32x4 v = acc[ai][bj][m][n];
;                         if (mode >= 5) { v += *(const f32x4*)(bias + col0 + bj * HALF + n * 16);
; #pragma unroll
;                             for (int q = 0; q < 4; ++q) { const float sg = __builtin_amdgcn_rcpf(1.f + __expf(-v[q])); v[q] = mode == 5 ? __expf(-0.6065306597126334f * sg) : sg; } }
;                         *(f32x4*)(rowp + bj * HALF + n * 16) = v; }
;                 asm volatile("" ::: "memory"); }
.LBB0_2498:
	v_pk_add_f32 v[26:27], v[26:27], v[246:247]
	v_pk_add_f32 v[24:25], v[24:25], v[244:245]
	v_mul_f32_e32 v26, 0xbfb8aa3b, v26
	v_mul_f32_e32 v24, 0xbfb8aa3b, v24
	v_mul_f32_e32 v25, 0xbfb8aa3b, v25
	v_mul_f32_e32 v27, 0xbfb8aa3b, v27
	v_exp_f32_e32 v24, v24
	v_exp_f32_e32 v25, v25
	v_exp_f32_e32 v26, v26
	v_exp_f32_e32 v27, v27
	v_add_f32_e32 v24, 1.0, v24
	v_add_f32_e32 v25, 1.0, v25
	v_add_f32_e32 v26, 1.0, v26
	v_add_f32_e32 v27, 1.0, v27
	v_rcp_f32_e32 v24, v24
	v_rcp_f32_e32 v25, v25
	v_rcp_f32_e32 v26, v26
	v_rcp_f32_e32 v27, v27
	v_mul_f32_e32 v28, 0xbf1b4598, v24
	v_mul_f32_e32 v29, 0xbf1b4598, v25
	v_mul_f32_e32 v30, 0xbf1b4598, v26
	v_mul_f32_e32 v31, 0xbf1b4598, v27
	v_mul_f32_e32 v28, 0x3fb8aa3b, v28
	v_mul_f32_e32 v29, 0x3fb8aa3b, v29
	v_mul_f32_e32 v30, 0x3fb8aa3b, v30
	v_mul_f32_e32 v31, 0x3fb8aa3b, v31
	v_exp_f32_e32 v28, v28
	v_exp_f32_e32 v29, v29
	v_exp_f32_e32 v30, v30
	v_exp_f32_e32 v31, v31
	v_cndmask_b32_e64 v24, v24, v28, s[8:9]
	v_cndmask_b32_e64 v25, v25, v29, s[8:9]
	v_cndmask_b32_e64 v26, v26, v30, s[8:9]
	v_cndmask_b32_e64 v27, v27, v31, s[8:9]
	flat_store_dwordx4 v[36:37], v[24:27] offset:512
	v_pk_add_f32 v[22:23], v[22:23], v[250:251]
	v_pk_add_f32 v[20:21], v[20:21], v[248:249]
	v_mul_f32_e32 v22, 0xbfb8aa3b, v22
	v_mul_f32_e32 v20, 0xbfb8aa3b, v20
	v_mul_f32_e32 v21, 0xbfb8aa3b, v21
	v_mul_f32_e32 v23, 0xbfb8aa3b, v23
	v_exp_f32_e32 v20, v20
	v_exp_f32_e32 v21, v21
	v_exp_f32_e32 v22, v22
	v_exp_f32_e32 v23, v23
	v_add_f32_e32 v20, 1.0, v20
	v_add_f32_e32 v21, 1.0, v21
	v_add_f32_e32 v22, 1.0, v22
	v_add_f32_e32 v23, 1.0, v23
	v_rcp_f32_e32 v20, v20
	v_rcp_f32_e32 v21, v21
	v_rcp_f32_e32 v22, v22
	v_rcp_f32_e32 v23, v23
	v_mul_f32_e32 v24, 0xbf1b4598, v20
	v_mul_f32_e32 v25, 0xbf1b4598, v21
	v_mul_f32_e32 v26, 0xbf1b4598, v22
	v_mul_f32_e32 v27, 0xbf1b4598, v23
	v_mul_f32_e32 v24, 0x3fb8aa3b, v24
	v_mul_f32_e32 v25, 0x3fb8aa3b, v25
	v_mul_f32_e32 v26, 0x3fb8aa3b, v26
	v_mul_f32_e32 v27, 0x3fb8aa3b, v27
	v_exp_f32_e32 v24, v24
	v_exp_f32_e32 v25, v25
	v_exp_f32_e32 v26, v26
	v_exp_f32_e32 v27, v27
	v_cndmask_b32_e64 v20, v20, v24, s[8:9]
	v_cndmask_b32_e64 v21, v21, v25, s[8:9]
	v_cndmask_b32_e64 v22, v22, v26, s[8:9]
	v_cndmask_b32_e64 v23, v23, v27, s[8:9]

; __device__ __forceinline__ void epilogue(const f32x4 (&acc)[2][2][4][2], const Unit& u, LAS unsigned char* lds, int wr, int wc, int fr, int fq) {
;     ...
;             for (int m = 0; m < 4; ++m) { float* rowp = C + (size_t)(row0 + ai * HALF + m * 16) * ldc + col0;
; #pragma unroll
;                 for (int bj = 0; bj < 2; ++bj)
; #pragma unroll
;                     for (int n = 0; n < 2; ++n) { f32x4 v = acc[ai][bj][m][n];
;                         if (mode >= 5) { v += *(const f32x4*)(bias + col0 + bj * HALF + n * 16);
; #pragma unroll
;                             for (int q = 0; q < 4; ++q) { const float sg = __builtin_amdgcn_rcpf(1.f + __expf(-v[q])); v[q] = mode == 5 ? __expf(-0.6065306597126334f * sg) : sg; } }
;                         *(f32x4*)(rowp + bj * HALF + n * 16) = v; }
;                 asm volatile("" ::: "memory"); }
.LBB0_2503:
	v_pk_add_f32 v[10:11], v[10:11], v[246:247]
	v_pk_add_f32 v[8:9], v[8:9], v[244:245]
	v_mul_f32_e32 v10, 0xbfb8aa3b, v10
	v_mul_f32_e32 v8, 0xbfb8aa3b, v8
	v_mul_f32_e32 v9, 0xbfb8aa3b, v9
	v_mul_f32_e32 v11, 0xbfb8aa3b, v11
	v_exp_f32_e32 v8, v8
	v_exp_f32_e32 v9, v9
	v_exp_f32_e32 v10, v10
	v_exp_f32_e32 v11, v11
	v_add_f32_e32 v8, 1.0, v8
	v_add_f32_e32 v9, 1.0, v9
	v_add_f32_e32 v10, 1.0, v10
	v_add_f32_e32 v11, 1.0, v11
	v_rcp_f32_e32 v8, v8
	v_rcp_f32_e32 v9, v9
	v_rcp_f32_e32 v10, v10
	v_rcp_f32_e32 v11, v11
	v_mul_f32_e32 v12, 0xbf1b4598, v8
	v_mul_f32_e32 v13, 0xbf1b4598, v9
	v_mul_f32_e32 v14, 0xbf1b4598, v10
	v_mul_f32_e32 v15, 0xbf1b4598, v11
	v_mul_f32_e32 v12, 0x3fb8aa3b, v12
	v_mul_f32_e32 v13, 0x3fb8aa3b, v13
	v_mul_f32_e32 v14, 0x3fb8aa3b, v14
	v_mul_f32_e32 v15, 0x3fb8aa3b, v15
	v_exp_f32_e32 v12, v12
	v_exp_f32_e32 v13, v13
	v_exp_f32_e32 v14, v14
	v_exp_f32_e32 v15, v15
	v_cndmask_b32_e64 v8, v8, v12, s[8:9]
	v_cndmask_b32_e64 v9, v9, v13, s[8:9]
	v_cndmask_b32_e64 v10, v10, v14, s[8:9]
	v_cndmask_b32_e64 v11, v11, v15, s[8:9]
	flat_store_dwordx4 v[20:21], v[8:11] offset:512
	v_pk_add_f32 v[6:7], v[6:7], v[250:251]
	v_pk_add_f32 v[4:5], v[4:5], v[248:249]
	v_mul_f32_e32 v6, 0xbfb8aa3b, v6
	v_mul_f32_e32 v4, 0xbfb8aa3b, v4
	v_mul_f32_e32 v5, 0xbfb8aa3b, v5
	v_mul_f32_e32 v7, 0xbfb8aa3b, v7
	v_exp_f32_e32 v4, v4
	v_exp_f32_e32 v5, v5
	v_exp_f32_e32 v6, v6
	v_exp_f32_e32 v7, v7
	v_add_f32_e32 v4, 1.0, v4
	v_add_f32_e32 v5, 1.0, v5
	v_add_f32_e32 v6, 1.0, v6
	v_add_f32_e32 v7, 1.0, v7
	v_rcp_f32_e32 v4, v4
	v_rcp_f32_e32 v5, v5
	v_rcp_f32_e32 v6, v6
	v_rcp_f32_e32 v7, v7
	v_mul_f32_e32 v8, 0xbf1b4598, v4
	v_mul_f32_e32 v9, 0xbf1b4598, v5
	v_mul_f32_e32 v10, 0xbf1b4598, v6
	v_mul_f32_e32 v11, 0xbf1b4598, v7
	v_mul_f32_e32 v8, 0x3fb8aa3b, v8
	v_mul_f32_e32 v9, 0x3fb8aa3b, v9
	v_mul_f32_e32 v10, 0x3fb8aa3b, v10
	v_mul_f32_e32 v11, 0x3fb8aa3b, v11
	v_exp_f32_e32 v8, v8
	v_exp_f32_e32 v9, v9
	v_exp_f32_e32 v10, v10
	v_exp_f32_e32 v11, v11
	v_cndmask_b32_e64 v4, v4, v8, s[8:9]
	v_cndmask_b32_e64 v5, v5, v9, s[8:9]
	v_cndmask_b32_e64 v6, v6, v10, s[8:9]
	v_cndmask_b32_e64 v7, v7, v11, s[8:9]

; __device__ __forceinline__ void epilogue(const f32x4 (&acc)[2][2][4][2], const Unit& u, LAS unsigned char* lds, int wr, int wc, int fr, int fq) {
;     ...
;     if (mode == 0 || mode >= 5) {
;         float* C = (float*)Cp; const float* bias = (const float*)rfl_ptr(jobs[u.j].bias);
; #pragma unroll
;         for (int ai = 0; ai < 2; ++ai)
; #pragma unroll
;             for (int m = 0; m < 4; ++m) { float* rowp = C + (size_t)(row0 + ai * HALF + m * 16) * ldc + col0;
; #pragma unroll
;                 for (int bj = 0; bj < 2; ++bj)
; #pragma unroll
;                     for (int n = 0; n < 2; ++n) { f32x4 v = acc[ai][bj][m][n];
;                         if (mode >= 5) { v += *(const f32x4*)(bias + col0 + bj * HALF + n * 16);
; #pragma unroll
;                             for (int q = 0; q < 4; ++q) { const float sg = __builtin_amdgcn_rcpf(1.f + __expf(-v[q])); v[q] = mode == 5 ? __expf(-0.6065306597126334f * sg) : sg; } }
;                         *(f32x4*)(rowp + bj * HALF + n * 16) = v; }
;                 asm volatile("" ::: "memory"); }
.LBB0_2509:
	flat_load_dwordx4 v[236:239], v[140:141]
	flat_load_dwordx4 v[240:243], v[140:141] offset:64
	flat_load_dwordx4 v[244:247], v[140:141] offset:512
	flat_load_dwordx4 v[248:251], v[140:141] offset:576
	s_waitcnt vmcnt(0) lgkmcnt(0)
	v_pk_add_f32 v[130:131], v[130:131], v[238:239]
	v_pk_add_f32 v[128:129], v[128:129], v[236:237]
	v_mul_f32_e32 v130, 0xbfb8aa3b, v130
	v_mul_f32_e32 v128, 0xbfb8aa3b, v128
	v_mul_f32_e32 v129, 0xbfb8aa3b, v129
	v_mul_f32_e32 v131, 0xbfb8aa3b, v131
	v_exp_f32_e32 v128, v128
	v_exp_f32_e32 v129, v129
	v_exp_f32_e32 v130, v130
	v_exp_f32_e32 v131, v131
	v_add_f32_e32 v128, 1.0, v128
	v_add_f32_e32 v129, 1.0, v129
	v_add_f32_e32 v130, 1.0, v130
	v_add_f32_e32 v131, 1.0, v131
	v_rcp_f32_e32 v128, v128
	v_rcp_f32_e32 v129, v129
	v_rcp_f32_e32 v130, v130
	v_rcp_f32_e32 v131, v131
	v_mul_f32_e32 v162, 0xbf1b4598, v128
	v_mul_f32_e32 v163, 0xbf1b4598, v129
	v_mul_f32_e32 v164, 0xbf1b4598, v130
	v_mul_f32_e32 v165, 0xbf1b4598, v131
	v_mul_f32_e32 v162, 0x3fb8aa3b, v162
	v_mul_f32_e32 v163, 0x3fb8aa3b, v163
	v_mul_f32_e32 v164, 0x3fb8aa3b, v164
	v_mul_f32_e32 v165, 0x3fb8aa3b, v165
	v_exp_f32_e32 v162, v162
	v_exp_f32_e32 v163, v163
	v_exp_f32_e32 v164, v164
	v_exp_f32_e32 v165, v165
	v_cndmask_b32_e64 v128, v128, v162, s[8:9]
	v_cndmask_b32_e64 v129, v129, v163, s[8:9]
	v_cndmask_b32_e64 v130, v130, v164, s[8:9]
	v_cndmask_b32_e64 v131, v131, v165, s[8:9]
	flat_store_dwordx4 v[144:145], v[128:131]
	v_pk_add_f32 v[126:127], v[126:127], v[242:243]
	v_pk_add_f32 v[124:125], v[124:125], v[240:241]
	v_mul_f32_e32 v126, 0xbfb8aa3b, v126
	v_mul_f32_e32 v124, 0xbfb8aa3b, v124
	v_mul_f32_e32 v125, 0xbfb8aa3b, v125
	v_mul_f32_e32 v127, 0xbfb8aa3b, v127
	v_exp_f32_e32 v124, v124
	v_exp_f32_e32 v125, v125
	v_exp_f32_e32 v126, v126
	v_exp_f32_e32 v127, v127
	v_add_f32_e32 v124, 1.0, v124
	v_add_f32_e32 v125, 1.0, v125
	v_add_f32_e32 v126, 1.0, v126
	v_add_f32_e32 v127, 1.0, v127
	v_rcp_f32_e32 v124, v124
	v_rcp_f32_e32 v125, v125
	v_rcp_f32_e32 v126, v126
	v_rcp_f32_e32 v127, v127
	v_mul_f32_e32 v128, 0xbf1b4598, v124
	v_mul_f32_e32 v129, 0xbf1b4598, v125
	v_mul_f32_e32 v130, 0xbf1b4598, v126
	v_mul_f32_e32 v131, 0xbf1b4598, v127
	v_mul_f32_e32 v128, 0x3fb8aa3b, v128
	v_mul_f32_e32 v129, 0x3fb8aa3b, v129
	v_mul_f32_e32 v130, 0x3fb8aa3b, v130
	v_mul_f32_e32 v131, 0x3fb8aa3b, v131
	v_exp_f32_e32 v128, v128
	v_exp_f32_e32 v129, v129
	v_exp_f32_e32 v130, v130
	v_exp_f32_e32 v131, v131
	v_cndmask_b32_e64 v124, v124, v128, s[8:9]
	v_cndmask_b32_e64 v125, v125, v129, s[8:9]
	v_cndmask_b32_e64 v126, v126, v130, s[8:9]
	v_cndmask_b32_e64 v127, v127, v131, s[8:9]
	s_mov_b64 s[2:3], -1
	s_and_b64 vcc, exec, s[24:25]
	flat_store_dwordx4 v[144:145], v[124:127] offset:64
	s_cbranch_vccz .LBB0_2467

; __device__ __forceinline__ void epilogue(const f32x4 (&acc)[2][2][4][2], const Unit& u, LAS unsigned char* lds, int wr, int wc, int fr, int fq) {
;     ...
;             for (int m = 0; m < 4; ++m) { float* rowp = C + (size_t)(row0 + ai * HALF + m * 16) * ldc + col0;
; #pragma unroll
;                 for (int bj = 0; bj < 2; ++bj)
; #pragma unroll
;                     for (int n = 0; n < 2; ++n) { f32x4 v = acc[ai][bj][m][n];
;                         if (mode >= 5) { v += *(const f32x4*)(bias + col0 + bj * HALF + n * 16);
; #pragma unroll
;                             for (int q = 0; q < 4; ++q) { const float sg = __builtin_amdgcn_rcpf(1.f + __expf(-v[q])); v[q] = mode == 5 ? __expf(-0.6065306597126334f * sg) : sg; } }
;                         *(f32x4*)(rowp + bj * HALF + n * 16) = v; }
;                 asm volatile("" ::: "memory"); }
.LBB0_2512:
	v_pk_add_f32 v[114:115], v[114:115], v[238:239]
	v_pk_add_f32 v[112:113], v[112:113], v[236:237]
	v_mul_f32_e32 v114, 0xbfb8aa3b, v114
	v_mul_f32_e32 v112, 0xbfb8aa3b, v112
	v_mul_f32_e32 v113, 0xbfb8aa3b, v113
	v_mul_f32_e32 v115, 0xbfb8aa3b, v115
	v_exp_f32_e32 v112, v112
	v_exp_f32_e32 v113, v113
	v_exp_f32_e32 v114, v114
	v_exp_f32_e32 v115, v115
	v_add_f32_e32 v112, 1.0, v112
	v_add_f32_e32 v113, 1.0, v113
	v_add_f32_e32 v114, 1.0, v114
	v_add_f32_e32 v115, 1.0, v115
	v_rcp_f32_e32 v112, v112
	v_rcp_f32_e32 v113, v113
	v_rcp_f32_e32 v114, v114
	v_rcp_f32_e32 v115, v115
	v_mul_f32_e32 v118, 0xbf1b4598, v112
	v_mul_f32_e32 v119, 0xbf1b4598, v113
	v_mul_f32_e32 v120, 0xbf1b4598, v114
	v_mul_f32_e32 v121, 0xbf1b4598, v115
	v_mul_f32_e32 v118, 0x3fb8aa3b, v118
	v_mul_f32_e32 v119, 0x3fb8aa3b, v119
	v_mul_f32_e32 v120, 0x3fb8aa3b, v120
	v_mul_f32_e32 v121, 0x3fb8aa3b, v121
	v_exp_f32_e32 v118, v118
	v_exp_f32_e32 v119, v119
	v_exp_f32_e32 v120, v120
	v_exp_f32_e32 v121, v121
	v_cndmask_b32_e64 v112, v112, v118, s[8:9]
	v_cndmask_b32_e64 v113, v113, v119, s[8:9]
	v_cndmask_b32_e64 v114, v114, v120, s[8:9]
	v_cndmask_b32_e64 v115, v115, v121, s[8:9]
	flat_store_dwordx4 v[116:117], v[112:115]
	v_pk_add_f32 v[110:111], v[110:111], v[242:243]
	v_pk_add_f32 v[108:109], v[108:109], v[240:241]
	v_mul_f32_e32 v110, 0xbfb8aa3b, v110
	v_mul_f32_e32 v108, 0xbfb8aa3b, v108
	v_mul_f32_e32 v109, 0xbfb8aa3b, v109
	v_mul_f32_e32 v111, 0xbfb8aa3b, v111
	v_exp_f32_e32 v108, v108
	v_exp_f32_e32 v109, v109
	v_exp_f32_e32 v110, v110
	v_exp_f32_e32 v111, v111
	v_add_f32_e32 v108, 1.0, v108
	v_add_f32_e32 v109, 1.0, v109
	v_add_f32_e32 v110, 1.0, v110
	v_add_f32_e32 v111, 1.0, v111
	v_rcp_f32_e32 v108, v108
	v_rcp_f32_e32 v109, v109
	v_rcp_f32_e32 v110, v110
	v_rcp_f32_e32 v111, v111
	v_mul_f32_e32 v112, 0xbf1b4598, v108
	v_mul_f32_e32 v113, 0xbf1b4598, v109
	v_mul_f32_e32 v114, 0xbf1b4598, v110
	v_mul_f32_e32 v115, 0xbf1b4598, v111
	v_mul_f32_e32 v112, 0x3fb8aa3b, v112
	v_mul_f32_e32 v113, 0x3fb8aa3b, v113
	v_mul_f32_e32 v114, 0x3fb8aa3b, v114
	v_mul_f32_e32 v115, 0x3fb8aa3b, v115
	v_exp_f32_e32 v112, v112
	v_exp_f32_e32 v113, v113
	v_exp_f32_e32 v114, v114
	v_exp_f32_e32 v115, v115
	v_cndmask_b32_e64 v108, v108, v112, s[8:9]
	v_cndmask_b32_e64 v109, v109, v113, s[8:9]
	v_cndmask_b32_e64 v110, v110, v114, s[8:9]
	v_cndmask_b32_e64 v111, v111, v115, s[8:9]
	s_mov_b64 s[2:3], -1
	s_and_b64 vcc, exec, s[24:25]
	flat_store_dwordx4 v[116:117], v[108:111] offset:64
	s_cbranch_vccz .LBB0_2472

; __device__ __forceinline__ void epilogue(const f32x4 (&acc)[2][2][4][2], const Unit& u, LAS unsigned char* lds, int wr, int wc, int fr, int fq) {
;     ...
;             for (int m = 0; m < 4; ++m) { float* rowp = C + (size_t)(row0 + ai * HALF + m * 16) * ldc + col0;
; #pragma unroll
;                 for (int bj = 0; bj < 2; ++bj)
; #pragma unroll
;                     for (int n = 0; n < 2; ++n) { f32x4 v = acc[ai][bj][m][n];
;                         if (mode >= 5) { v += *(const f32x4*)(bias + col0 + bj * HALF + n * 16);
; #pragma unroll
;                             for (int q = 0; q < 4; ++q) { const float sg = __builtin_amdgcn_rcpf(1.f + __expf(-v[q])); v[q] = mode == 5 ? __expf(-0.6065306597126334f * sg) : sg; } }
;                         *(f32x4*)(rowp + bj * HALF + n * 16) = v; }
;                 asm volatile("" ::: "memory"); }
.LBB0_2515:
	v_pk_add_f32 v[98:99], v[98:99], v[238:239]
	v_pk_add_f32 v[96:97], v[96:97], v[236:237]
	v_mul_f32_e32 v98, 0xbfb8aa3b, v98
	v_mul_f32_e32 v96, 0xbfb8aa3b, v96
	v_mul_f32_e32 v97, 0xbfb8aa3b, v97
	v_mul_f32_e32 v99, 0xbfb8aa3b, v99
	v_exp_f32_e32 v96, v96
	v_exp_f32_e32 v97, v97
	v_exp_f32_e32 v98, v98
	v_exp_f32_e32 v99, v99
	v_add_f32_e32 v96, 1.0, v96
	v_add_f32_e32 v97, 1.0, v97
	v_add_f32_e32 v98, 1.0, v98
	v_add_f32_e32 v99, 1.0, v99
	v_rcp_f32_e32 v96, v96
	v_rcp_f32_e32 v97, v97
	v_rcp_f32_e32 v98, v98
	v_rcp_f32_e32 v99, v99
	v_mul_f32_e32 v102, 0xbf1b4598, v96
	v_mul_f32_e32 v103, 0xbf1b4598, v97
	v_mul_f32_e32 v104, 0xbf1b4598, v98
	v_mul_f32_e32 v105, 0xbf1b4598, v99
	v_mul_f32_e32 v102, 0x3fb8aa3b, v102
	v_mul_f32_e32 v103, 0x3fb8aa3b, v103
	v_mul_f32_e32 v104, 0x3fb8aa3b, v104
	v_mul_f32_e32 v105, 0x3fb8aa3b, v105
	v_exp_f32_e32 v102, v102
	v_exp_f32_e32 v103, v103
	v_exp_f32_e32 v104, v104
	v_exp_f32_e32 v105, v105
	v_cndmask_b32_e64 v96, v96, v102, s[8:9]
	v_cndmask_b32_e64 v97, v97, v103, s[8:9]
	v_cndmask_b32_e64 v98, v98, v104, s[8:9]
	v_cndmask_b32_e64 v99, v99, v105, s[8:9]
	flat_store_dwordx4 v[100:101], v[96:99]
	v_pk_add_f32 v[94:95], v[94:95], v[242:243]
	v_pk_add_f32 v[92:93], v[92:93], v[240:241]
	v_mul_f32_e32 v94, 0xbfb8aa3b, v94
	v_mul_f32_e32 v92, 0xbfb8aa3b, v92
	v_mul_f32_e32 v93, 0xbfb8aa3b, v93
	v_mul_f32_e32 v95, 0xbfb8aa3b, v95
	v_exp_f32_e32 v92, v92
	v_exp_f32_e32 v93, v93
	v_exp_f32_e32 v94, v94
	v_exp_f32_e32 v95, v95
	v_add_f32_e32 v92, 1.0, v92
	v_add_f32_e32 v93, 1.0, v93
	v_add_f32_e32 v94, 1.0, v94
	v_add_f32_e32 v95, 1.0, v95
	v_rcp_f32_e32 v92, v92
	v_rcp_f32_e32 v93, v93
	v_rcp_f32_e32 v94, v94
	v_rcp_f32_e32 v95, v95
	v_mul_f32_e32 v96, 0xbf1b4598, v92
	v_mul_f32_e32 v97, 0xbf1b4598, v93
	v_mul_f32_e32 v98, 0xbf1b4598, v94
	v_mul_f32_e32 v99, 0xbf1b4598, v95
	v_mul_f32_e32 v96, 0x3fb8aa3b, v96
	v_mul_f32_e32 v97, 0x3fb8aa3b, v97
	v_mul_f32_e32 v98, 0x3fb8aa3b, v98
	v_mul_f32_e32 v99, 0x3fb8aa3b, v99
	v_exp_f32_e32 v96, v96
	v_exp_f32_e32 v97, v97
	v_exp_f32_e32 v98, v98
	v_exp_f32_e32 v99, v99
	v_cndmask_b32_e64 v92, v92, v96, s[8:9]
	v_cndmask_b32_e64 v93, v93, v97, s[8:9]
	v_cndmask_b32_e64 v94, v94, v98, s[8:9]
	v_cndmask_b32_e64 v95, v95, v99, s[8:9]
	s_mov_b64 s[2:3], -1
	s_and_b64 vcc, exec, s[24:25]
	flat_store_dwordx4 v[100:101], v[92:95] offset:64
	s_cbranch_vccz .LBB0_2477

; __device__ __forceinline__ void epilogue(const f32x4 (&acc)[2][2][4][2], const Unit& u, LAS unsigned char* lds, int wr, int wc, int fr, int fq) {
;     ...
;             for (int m = 0; m < 4; ++m) { float* rowp = C + (size_t)(row0 + ai * HALF + m * 16) * ldc + col0;
; #pragma unroll
;                 for (int bj = 0; bj < 2; ++bj)
; #pragma unroll
;                     for (int n = 0; n < 2; ++n) { f32x4 v = acc[ai][bj][m][n];
;                         if (mode >= 5) { v += *(const f32x4*)(bias + col0 + bj * HALF + n * 16);
; #pragma unroll
;                             for (int q = 0; q < 4; ++q) { const float sg = __builtin_amdgcn_rcpf(1.f + __expf(-v[q])); v[q] = mode == 5 ? __expf(-0.6065306597126334f * sg) : sg; } }
;                         *(f32x4*)(rowp + bj * HALF + n * 16) = v; }
;                 asm volatile("" ::: "memory"); }
.LBB0_2518:
	v_pk_add_f32 v[82:83], v[82:83], v[238:239]
	v_pk_add_f32 v[80:81], v[80:81], v[236:237]
	v_mul_f32_e32 v82, 0xbfb8aa3b, v82
	v_mul_f32_e32 v80, 0xbfb8aa3b, v80
	v_mul_f32_e32 v81, 0xbfb8aa3b, v81
	v_mul_f32_e32 v83, 0xbfb8aa3b, v83
	v_exp_f32_e32 v80, v80
	v_exp_f32_e32 v81, v81
	v_exp_f32_e32 v82, v82
	v_exp_f32_e32 v83, v83
	v_add_f32_e32 v80, 1.0, v80
	v_add_f32_e32 v81, 1.0, v81
	v_add_f32_e32 v82, 1.0, v82
	v_add_f32_e32 v83, 1.0, v83
	v_rcp_f32_e32 v80, v80
	v_rcp_f32_e32 v81, v81
	v_rcp_f32_e32 v82, v82
	v_rcp_f32_e32 v83, v83
	v_mul_f32_e32 v86, 0xbf1b4598, v80
	v_mul_f32_e32 v87, 0xbf1b4598, v81
	v_mul_f32_e32 v88, 0xbf1b4598, v82
	v_mul_f32_e32 v89, 0xbf1b4598, v83
	v_mul_f32_e32 v86, 0x3fb8aa3b, v86
	v_mul_f32_e32 v87, 0x3fb8aa3b, v87
	v_mul_f32_e32 v88, 0x3fb8aa3b, v88
	v_mul_f32_e32 v89, 0x3fb8aa3b, v89
	v_exp_f32_e32 v86, v86
	v_exp_f32_e32 v87, v87
	v_exp_f32_e32 v88, v88
	v_exp_f32_e32 v89, v89
	v_cndmask_b32_e64 v80, v80, v86, s[8:9]
	v_cndmask_b32_e64 v81, v81, v87, s[8:9]
	v_cndmask_b32_e64 v82, v82, v88, s[8:9]
	v_cndmask_b32_e64 v83, v83, v89, s[8:9]
	flat_store_dwordx4 v[84:85], v[80:83]
	v_pk_add_f32 v[78:79], v[78:79], v[242:243]
	v_pk_add_f32 v[76:77], v[76:77], v[240:241]
	v_mul_f32_e32 v78, 0xbfb8aa3b, v78
	v_mul_f32_e32 v76, 0xbfb8aa3b, v76
	v_mul_f32_e32 v77, 0xbfb8aa3b, v77
	v_mul_f32_e32 v79, 0xbfb8aa3b, v79
	v_exp_f32_e32 v76, v76
	v_exp_f32_e32 v77, v77
	v_exp_f32_e32 v78, v78
	v_exp_f32_e32 v79, v79
	v_add_f32_e32 v76, 1.0, v76
	v_add_f32_e32 v77, 1.0, v77
	v_add_f32_e32 v78, 1.0, v78
	v_add_f32_e32 v79, 1.0, v79
	v_rcp_f32_e32 v76, v76
	v_rcp_f32_e32 v77, v77
	v_rcp_f32_e32 v78, v78
	v_rcp_f32_e32 v79, v79
	v_mul_f32_e32 v80, 0xbf1b4598, v76
	v_mul_f32_e32 v81, 0xbf1b4598, v77
	v_mul_f32_e32 v82, 0xbf1b4598, v78
	v_mul_f32_e32 v83, 0xbf1b4598, v79
	v_mul_f32_e32 v80, 0x3fb8aa3b, v80
	v_mul_f32_e32 v81, 0x3fb8aa3b, v81
	v_mul_f32_e32 v82, 0x3fb8aa3b, v82
	v_mul_f32_e32 v83, 0x3fb8aa3b, v83
	v_exp_f32_e32 v80, v80
	v_exp_f32_e32 v81, v81
	v_exp_f32_e32 v82, v82
	v_exp_f32_e32 v83, v83
	v_cndmask_b32_e64 v76, v76, v80, s[8:9]
	v_cndmask_b32_e64 v77, v77, v81, s[8:9]
	v_cndmask_b32_e64 v78, v78, v82, s[8:9]
	v_cndmask_b32_e64 v79, v79, v83, s[8:9]
	s_mov_b64 s[2:3], -1
	s_and_b64 vcc, exec, s[24:25]
	flat_store_dwordx4 v[84:85], v[76:79] offset:64
	s_cbranch_vccz .LBB0_2482

; __device__ __forceinline__ void epilogue(const f32x4 (&acc)[2][2][4][2], const Unit& u, LAS unsigned char* lds, int wr, int wc, int fr, int fq) {
;     ...
;             for (int m = 0; m < 4; ++m) { float* rowp = C + (size_t)(row0 + ai * HALF + m * 16) * ldc + col0;
; #pragma unroll
;                 for (int bj = 0; bj < 2; ++bj)
; #pragma unroll
;                     for (int n = 0; n < 2; ++n) { f32x4 v = acc[ai][bj][m][n];
;                         if (mode >= 5) { v += *(const f32x4*)(bias + col0 + bj * HALF + n * 16);
; #pragma unroll
;                             for (int q = 0; q < 4; ++q) { const float sg = __builtin_amdgcn_rcpf(1.f + __expf(-v[q])); v[q] = mode == 5 ? __expf(-0.6065306597126334f * sg) : sg; } }
;                         *(f32x4*)(rowp + bj * HALF + n * 16) = v; }
;                 asm volatile("" ::: "memory"); }
.LBB0_2521:
	v_pk_add_f32 v[66:67], v[66:67], v[238:239]
	v_pk_add_f32 v[64:65], v[64:65], v[236:237]
	v_mul_f32_e32 v66, 0xbfb8aa3b, v66
	v_mul_f32_e32 v64, 0xbfb8aa3b, v64
	v_mul_f32_e32 v65, 0xbfb8aa3b, v65
	v_mul_f32_e32 v67, 0xbfb8aa3b, v67
	v_exp_f32_e32 v64, v64
	v_exp_f32_e32 v65, v65
	v_exp_f32_e32 v66, v66
	v_exp_f32_e32 v67, v67
	v_add_f32_e32 v64, 1.0, v64
	v_add_f32_e32 v65, 1.0, v65
	v_add_f32_e32 v66, 1.0, v66
	v_add_f32_e32 v67, 1.0, v67
	v_rcp_f32_e32 v64, v64
	v_rcp_f32_e32 v65, v65
	v_rcp_f32_e32 v66, v66
	v_rcp_f32_e32 v67, v67
	v_mul_f32_e32 v70, 0xbf1b4598, v64
	v_mul_f32_e32 v71, 0xbf1b4598, v65
	v_mul_f32_e32 v72, 0xbf1b4598, v66
	v_mul_f32_e32 v73, 0xbf1b4598, v67
	v_mul_f32_e32 v70, 0x3fb8aa3b, v70
	v_mul_f32_e32 v71, 0x3fb8aa3b, v71
	v_mul_f32_e32 v72, 0x3fb8aa3b, v72
	v_mul_f32_e32 v73, 0x3fb8aa3b, v73
	v_exp_f32_e32 v70, v70
	v_exp_f32_e32 v71, v71
	v_exp_f32_e32 v72, v72
	v_exp_f32_e32 v73, v73
	v_cndmask_b32_e64 v64, v64, v70, s[8:9]
	v_cndmask_b32_e64 v65, v65, v71, s[8:9]
	v_cndmask_b32_e64 v66, v66, v72, s[8:9]
	v_cndmask_b32_e64 v67, v67, v73, s[8:9]
	flat_store_dwordx4 v[68:69], v[64:67]
	v_pk_add_f32 v[62:63], v[62:63], v[242:243]
	v_pk_add_f32 v[60:61], v[60:61], v[240:241]
	v_mul_f32_e32 v62, 0xbfb8aa3b, v62
	v_mul_f32_e32 v60, 0xbfb8aa3b, v60
	v_mul_f32_e32 v61, 0xbfb8aa3b, v61
	v_mul_f32_e32 v63, 0xbfb8aa3b, v63
	v_exp_f32_e32 v60, v60
	v_exp_f32_e32 v61, v61
	v_exp_f32_e32 v62, v62
	v_exp_f32_e32 v63, v63
	v_add_f32_e32 v60, 1.0, v60
	v_add_f32_e32 v61, 1.0, v61
	v_add_f32_e32 v62, 1.0, v62
	v_add_f32_e32 v63, 1.0, v63
	v_rcp_f32_e32 v60, v60
	v_rcp_f32_e32 v61, v61
	v_rcp_f32_e32 v62, v62
	v_rcp_f32_e32 v63, v63
	v_mul_f32_e32 v64, 0xbf1b4598, v60
	v_mul_f32_e32 v65, 0xbf1b4598, v61
	v_mul_f32_e32 v66, 0xbf1b4598, v62
	v_mul_f32_e32 v67, 0xbf1b4598, v63
	v_mul_f32_e32 v64, 0x3fb8aa3b, v64
	v_mul_f32_e32 v65, 0x3fb8aa3b, v65
	v_mul_f32_e32 v66, 0x3fb8aa3b, v66
	v_mul_f32_e32 v67, 0x3fb8aa3b, v67
	v_exp_f32_e32 v64, v64
	v_exp_f32_e32 v65, v65
	v_exp_f32_e32 v66, v66
	v_exp_f32_e32 v67, v67
	v_cndmask_b32_e64 v60, v60, v64, s[8:9]
	v_cndmask_b32_e64 v61, v61, v65, s[8:9]
	v_cndmask_b32_e64 v62, v62, v66, s[8:9]
	v_cndmask_b32_e64 v63, v63, v67, s[8:9]
	s_mov_b64 s[2:3], -1
	s_and_b64 vcc, exec, s[24:25]
	flat_store_dwordx4 v[68:69], v[60:63] offset:64
	s_cbranch_vccz .LBB0_2487

; __device__ __forceinline__ void epilogue(const f32x4 (&acc)[2][2][4][2], const Unit& u, LAS unsigned char* lds, int wr, int wc, int fr, int fq) {
;     ...
;             for (int m = 0; m < 4; ++m) { float* rowp = C + (size_t)(row0 + ai * HALF + m * 16) * ldc + col0;
; #pragma unroll
;                 for (int bj = 0; bj < 2; ++bj)
; #pragma unroll
;                     for (int n = 0; n < 2; ++n) { f32x4 v = acc[ai][bj][m][n];
;                         if (mode >= 5) { v += *(const f32x4*)(bias + col0 + bj * HALF + n * 16);
; #pragma unroll
;                             for (int q = 0; q < 4; ++q) { const float sg = __builtin_amdgcn_rcpf(1.f + __expf(-v[q])); v[q] = mode == 5 ? __expf(-0.6065306597126334f * sg) : sg; } }
;                         *(f32x4*)(rowp + bj * HALF + n * 16) = v; }
;                 asm volatile("" ::: "memory"); }
.LBB0_2524:
	v_pk_add_f32 v[50:51], v[50:51], v[238:239]
	v_pk_add_f32 v[48:49], v[48:49], v[236:237]
	v_mul_f32_e32 v50, 0xbfb8aa3b, v50
	v_mul_f32_e32 v48, 0xbfb8aa3b, v48
	v_mul_f32_e32 v49, 0xbfb8aa3b, v49
	v_mul_f32_e32 v51, 0xbfb8aa3b, v51
	v_exp_f32_e32 v48, v48
	v_exp_f32_e32 v49, v49
	v_exp_f32_e32 v50, v50
	v_exp_f32_e32 v51, v51
	v_add_f32_e32 v48, 1.0, v48
	v_add_f32_e32 v49, 1.0, v49
	v_add_f32_e32 v50, 1.0, v50
	v_add_f32_e32 v51, 1.0, v51
	v_rcp_f32_e32 v48, v48
	v_rcp_f32_e32 v49, v49
	v_rcp_f32_e32 v50, v50
	v_rcp_f32_e32 v51, v51
	v_mul_f32_e32 v54, 0xbf1b4598, v48
	v_mul_f32_e32 v55, 0xbf1b4598, v49
	v_mul_f32_e32 v56, 0xbf1b4598, v50
	v_mul_f32_e32 v57, 0xbf1b4598, v51
	v_mul_f32_e32 v54, 0x3fb8aa3b, v54
	v_mul_f32_e32 v55, 0x3fb8aa3b, v55
	v_mul_f32_e32 v56, 0x3fb8aa3b, v56
	v_mul_f32_e32 v57, 0x3fb8aa3b, v57
	v_exp_f32_e32 v54, v54
	v_exp_f32_e32 v55, v55
	v_exp_f32_e32 v56, v56
	v_exp_f32_e32 v57, v57
	v_cndmask_b32_e64 v48, v48, v54, s[8:9]
	v_cndmask_b32_e64 v49, v49, v55, s[8:9]
	v_cndmask_b32_e64 v50, v50, v56, s[8:9]
	v_cndmask_b32_e64 v51, v51, v57, s[8:9]
	flat_store_dwordx4 v[52:53], v[48:51]
	v_pk_add_f32 v[46:47], v[46:47], v[242:243]
	v_pk_add_f32 v[44:45], v[44:45], v[240:241]
	v_mul_f32_e32 v46, 0xbfb8aa3b, v46
	v_mul_f32_e32 v44, 0xbfb8aa3b, v44
	v_mul_f32_e32 v45, 0xbfb8aa3b, v45
	v_mul_f32_e32 v47, 0xbfb8aa3b, v47
	v_exp_f32_e32 v44, v44
	v_exp_f32_e32 v45, v45
	v_exp_f32_e32 v46, v46
	v_exp_f32_e32 v47, v47
	v_add_f32_e32 v44, 1.0, v44
	v_add_f32_e32 v45, 1.0, v45
	v_add_f32_e32 v46, 1.0, v46
	v_add_f32_e32 v47, 1.0, v47
	v_rcp_f32_e32 v44, v44
	v_rcp_f32_e32 v45, v45
	v_rcp_f32_e32 v46, v46
	v_rcp_f32_e32 v47, v47
	v_mul_f32_e32 v48, 0xbf1b4598, v44
	v_mul_f32_e32 v49, 0xbf1b4598, v45
	v_mul_f32_e32 v50, 0xbf1b4598, v46
	v_mul_f32_e32 v51, 0xbf1b4598, v47
	v_mul_f32_e32 v48, 0x3fb8aa3b, v48
	v_mul_f32_e32 v49, 0x3fb8aa3b, v49
	v_mul_f32_e32 v50, 0x3fb8aa3b, v50
	v_mul_f32_e32 v51, 0x3fb8aa3b, v51
	v_exp_f32_e32 v48, v48
	v_exp_f32_e32 v49, v49
	v_exp_f32_e32 v50, v50
	v_exp_f32_e32 v51, v51
	v_cndmask_b32_e64 v44, v44, v48, s[8:9]
	v_cndmask_b32_e64 v45, v45, v49, s[8:9]
	v_cndmask_b32_e64 v46, v46, v50, s[8:9]
	v_cndmask_b32_e64 v47, v47, v51, s[8:9]
	s_mov_b64 s[2:3], -1
	s_and_b64 vcc, exec, s[24:25]
	flat_store_dwordx4 v[52:53], v[44:47] offset:64
	s_cbranch_vccz .LBB0_2492

; __device__ __forceinline__ void epilogue(const f32x4 (&acc)[2][2][4][2], const Unit& u, LAS unsigned char* lds, int wr, int wc, int fr, int fq) {
;     ...
;             for (int m = 0; m < 4; ++m) { float* rowp = C + (size_t)(row0 + ai * HALF + m * 16) * ldc + col0;
; #pragma unroll
;                 for (int bj = 0; bj < 2; ++bj)
; #pragma unroll
;                     for (int n = 0; n < 2; ++n) { f32x4 v = acc[ai][bj][m][n];
;                         if (mode >= 5) { v += *(const f32x4*)(bias + col0 + bj * HALF + n * 16);
; #pragma unroll
;                             for (int q = 0; q < 4; ++q) { const float sg = __builtin_amdgcn_rcpf(1.f + __expf(-v[q])); v[q] = mode == 5 ? __expf(-0.6065306597126334f * sg) : sg; } }
;                         *(f32x4*)(rowp + bj * HALF + n * 16) = v; }
;                 asm volatile("" ::: "memory"); }
.LBB0_2527:
	v_pk_add_f32 v[34:35], v[34:35], v[238:239]
	v_pk_add_f32 v[32:33], v[32:33], v[236:237]
	v_mul_f32_e32 v34, 0xbfb8aa3b, v34
	v_mul_f32_e32 v32, 0xbfb8aa3b, v32
	v_mul_f32_e32 v33, 0xbfb8aa3b, v33
	v_mul_f32_e32 v35, 0xbfb8aa3b, v35
	v_exp_f32_e32 v32, v32
	v_exp_f32_e32 v33, v33
	v_exp_f32_e32 v34, v34
	v_exp_f32_e32 v35, v35
	v_add_f32_e32 v32, 1.0, v32
	v_add_f32_e32 v33, 1.0, v33
	v_add_f32_e32 v34, 1.0, v34
	v_add_f32_e32 v35, 1.0, v35
	v_rcp_f32_e32 v32, v32
	v_rcp_f32_e32 v33, v33
	v_rcp_f32_e32 v34, v34
	v_rcp_f32_e32 v35, v35
	v_mul_f32_e32 v38, 0xbf1b4598, v32
	v_mul_f32_e32 v39, 0xbf1b4598, v33
	v_mul_f32_e32 v40, 0xbf1b4598, v34
	v_mul_f32_e32 v41, 0xbf1b4598, v35
	v_mul_f32_e32 v38, 0x3fb8aa3b, v38
	v_mul_f32_e32 v39, 0x3fb8aa3b, v39
	v_mul_f32_e32 v40, 0x3fb8aa3b, v40
	v_mul_f32_e32 v41, 0x3fb8aa3b, v41
	v_exp_f32_e32 v38, v38
	v_exp_f32_e32 v39, v39
	v_exp_f32_e32 v40, v40
	v_exp_f32_e32 v41, v41
	v_cndmask_b32_e64 v32, v32, v38, s[8:9]
	v_cndmask_b32_e64 v33, v33, v39, s[8:9]
	v_cndmask_b32_e64 v34, v34, v40, s[8:9]
	v_cndmask_b32_e64 v35, v35, v41, s[8:9]
	flat_store_dwordx4 v[36:37], v[32:35]
	v_pk_add_f32 v[30:31], v[30:31], v[242:243]
	v_pk_add_f32 v[28:29], v[28:29], v[240:241]
	v_mul_f32_e32 v30, 0xbfb8aa3b, v30
	v_mul_f32_e32 v28, 0xbfb8aa3b, v28
	v_mul_f32_e32 v29, 0xbfb8aa3b, v29
	v_mul_f32_e32 v31, 0xbfb8aa3b, v31
	v_exp_f32_e32 v28, v28
	v_exp_f32_e32 v29, v29
	v_exp_f32_e32 v30, v30
	v_exp_f32_e32 v31, v31
	v_add_f32_e32 v28, 1.0, v28
	v_add_f32_e32 v29, 1.0, v29
	v_add_f32_e32 v30, 1.0, v30
	v_add_f32_e32 v31, 1.0, v31
	v_rcp_f32_e32 v28, v28
	v_rcp_f32_e32 v29, v29
	v_rcp_f32_e32 v30, v30
	v_rcp_f32_e32 v31, v31
	v_mul_f32_e32 v32, 0xbf1b4598, v28
	v_mul_f32_e32 v33, 0xbf1b4598, v29
	v_mul_f32_e32 v34, 0xbf1b4598, v30
	v_mul_f32_e32 v35, 0xbf1b4598, v31
	v_mul_f32_e32 v32, 0x3fb8aa3b, v32
	v_mul_f32_e32 v33, 0x3fb8aa3b, v33
	v_mul_f32_e32 v34, 0x3fb8aa3b, v34
	v_mul_f32_e32 v35, 0x3fb8aa3b, v35
	v_exp_f32_e32 v32, v32
	v_exp_f32_e32 v33, v33
	v_exp_f32_e32 v34, v34
	v_exp_f32_e32 v35, v35
	v_cndmask_b32_e64 v28, v28, v32, s[8:9]
	v_cndmask_b32_e64 v29, v29, v33, s[8:9]
	v_cndmask_b32_e64 v30, v30, v34, s[8:9]
	v_cndmask_b32_e64 v31, v31, v35, s[8:9]
	s_mov_b64 s[2:3], -1
	s_and_b64 vcc, exec, s[24:25]
	flat_store_dwordx4 v[36:37], v[28:31] offset:64
	s_cbranch_vccz .LBB0_2497

; __device__ __forceinline__ void epilogue(const f32x4 (&acc)[2][2][4][2], const Unit& u, LAS unsigned char* lds, int wr, int wc, int fr, int fq) {
;     ...
;             for (int m = 0; m < 4; ++m) { float* rowp = C + (size_t)(row0 + ai * HALF + m * 16) * ldc + col0;
; #pragma unroll
;                 for (int bj = 0; bj < 2; ++bj)
; #pragma unroll
;                     for (int n = 0; n < 2; ++n) { f32x4 v = acc[ai][bj][m][n];
;                         if (mode >= 5) { v += *(const f32x4*)(bias + col0 + bj * HALF + n * 16);
; #pragma unroll
;                             for (int q = 0; q < 4; ++q) { const float sg = __builtin_amdgcn_rcpf(1.f + __expf(-v[q])); v[q] = mode == 5 ? __expf(-0.6065306597126334f * sg) : sg; } }
;                         *(f32x4*)(rowp + bj * HALF + n * 16) = v; }
;                 asm volatile("" ::: "memory"); }
.LBB0_2530:
	v_pk_add_f32 v[18:19], v[18:19], v[238:239]
	v_pk_add_f32 v[16:17], v[16:17], v[236:237]
	v_mul_f32_e32 v18, 0xbfb8aa3b, v18
	v_mul_f32_e32 v16, 0xbfb8aa3b, v16
	v_mul_f32_e32 v17, 0xbfb8aa3b, v17
	v_mul_f32_e32 v19, 0xbfb8aa3b, v19
	v_exp_f32_e32 v16, v16
	v_exp_f32_e32 v17, v17
	v_exp_f32_e32 v18, v18
	v_exp_f32_e32 v19, v19
	v_add_f32_e32 v16, 1.0, v16
	v_add_f32_e32 v17, 1.0, v17
	v_add_f32_e32 v18, 1.0, v18
	v_add_f32_e32 v19, 1.0, v19
	v_rcp_f32_e32 v16, v16
	v_rcp_f32_e32 v17, v17
	v_rcp_f32_e32 v18, v18
	v_rcp_f32_e32 v19, v19
	v_mul_f32_e32 v22, 0xbf1b4598, v16
	v_mul_f32_e32 v23, 0xbf1b4598, v17
	v_mul_f32_e32 v24, 0xbf1b4598, v18
	v_mul_f32_e32 v25, 0xbf1b4598, v19
	v_mul_f32_e32 v22, 0x3fb8aa3b, v22
	v_mul_f32_e32 v23, 0x3fb8aa3b, v23
	v_mul_f32_e32 v24, 0x3fb8aa3b, v24
	v_mul_f32_e32 v25, 0x3fb8aa3b, v25
	v_exp_f32_e32 v22, v22
	v_exp_f32_e32 v23, v23
	v_exp_f32_e32 v24, v24
	v_exp_f32_e32 v25, v25
	v_cndmask_b32_e64 v16, v16, v22, s[8:9]
	v_cndmask_b32_e64 v17, v17, v23, s[8:9]
	v_cndmask_b32_e64 v18, v18, v24, s[8:9]
	v_cndmask_b32_e64 v19, v19, v25, s[8:9]
	flat_store_dwordx4 v[20:21], v[16:19]
	v_pk_add_f32 v[14:15], v[14:15], v[242:243]
	v_pk_add_f32 v[12:13], v[12:13], v[240:241]
	v_mul_f32_e32 v14, 0xbfb8aa3b, v14
	v_mul_f32_e32 v12, 0xbfb8aa3b, v12
	v_mul_f32_e32 v13, 0xbfb8aa3b, v13
	v_mul_f32_e32 v15, 0xbfb8aa3b, v15
	v_exp_f32_e32 v12, v12
	v_exp_f32_e32 v13, v13
	v_exp_f32_e32 v14, v14
	v_exp_f32_e32 v15, v15
	v_add_f32_e32 v12, 1.0, v12
	v_add_f32_e32 v13, 1.0, v13
	v_add_f32_e32 v14, 1.0, v14
	v_add_f32_e32 v15, 1.0, v15
	v_rcp_f32_e32 v12, v12
	v_rcp_f32_e32 v13, v13
	v_rcp_f32_e32 v14, v14
	v_rcp_f32_e32 v15, v15
	v_mul_f32_e32 v16, 0xbf1b4598, v12
	v_mul_f32_e32 v17, 0xbf1b4598, v13
	v_mul_f32_e32 v18, 0xbf1b4598, v14
	v_mul_f32_e32 v19, 0xbf1b4598, v15
	v_mul_f32_e32 v16, 0x3fb8aa3b, v16
	v_mul_f32_e32 v17, 0x3fb8aa3b, v17
	v_mul_f32_e32 v18, 0x3fb8aa3b, v18
	v_mul_f32_e32 v19, 0x3fb8aa3b, v19
	v_exp_f32_e32 v16, v16
	v_exp_f32_e32 v17, v17
	v_exp_f32_e32 v18, v18
	v_exp_f32_e32 v19, v19
	v_cndmask_b32_e64 v12, v12, v16, s[8:9]
	v_cndmask_b32_e64 v13, v13, v17, s[8:9]
	v_cndmask_b32_e64 v14, v14, v18, s[8:9]
	v_cndmask_b32_e64 v15, v15, v19, s[8:9]
	s_mov_b64 s[2:3], -1
	s_and_b64 vcc, exec, s[24:25]
	flat_store_dwordx4 v[20:21], v[12:15] offset:64
	s_cbranch_vccz .LBB0_2502

; #define LAS __attribute__((address_space(3)))
; __global__ void __launch_bounds__(512, 2) mega_fwd(Params p) {
;     extern __shared__ __attribute__((aligned(16))) unsigned char lds_raw[];
;     LAS unsigned char* lds = (LAS unsigned char*)lds_raw;
;     cg::grid_group grid = cg::this_grid();
	.amdhsa_kernel _Z8mega_fwd6Params
		.amdhsa_group_segment_fixed_size 0
		.amdhsa_private_segment_fixed_size 0
		.amdhsa_kernarg_size 592
		.amdhsa_user_sgpr_count 2
		.amdhsa_user_sgpr_dispatch_ptr 0
		.amdhsa_user_sgpr_queue_ptr 0
		.amdhsa_user_sgpr_kernarg_segment_ptr 1
		.amdhsa_user_sgpr_dispatch_id 0
		.amdhsa_user_sgpr_kernarg_preload_length 0
		.amdhsa_user_sgpr_kernarg_preload_offset 0
		.amdhsa_user_sgpr_private_segment_size 0
		.amdhsa_uses_dynamic_stack 0
		.amdhsa_enable_private_segment 0
		.amdhsa_system_sgpr_workgroup_id_x 1
		.amdhsa_system_sgpr_workgroup_id_y 0
		.amdhsa_system_sgpr_workgroup_id_z 0
		.amdhsa_system_sgpr_workgroup_info 0
		.amdhsa_system_vgpr_workitem_id 2
		.amdhsa_next_free_vgpr 252
		.amdhsa_next_free_sgpr 102
		.amdhsa_accum_offset 252
		.amdhsa_reserve_vcc 1
		.amdhsa_float_round_mode_32 0
		.amdhsa_float_round_mode_16_64 0
		.amdhsa_float_denorm_mode_32 3
		.amdhsa_float_denorm_mode_16_64 3
		.amdhsa_dx10_clamp 1
		.amdhsa_ieee_mode 1
		.amdhsa_fp16_overflow 0
		.amdhsa_tg_split 0
		.amdhsa_exception_fp_ieee_invalid_op 0
		.amdhsa_exception_fp_denorm_src 0
		.amdhsa_exception_fp_ieee_div_zero 0
		.amdhsa_exception_fp_ieee_overflow 0
		.amdhsa_exception_fp_ieee_underflow 0
		.amdhsa_exception_fp_ieee_inexact 0
		.amdhsa_exception_int_div_zero 0
	.end_amdhsa_kernel

; #define LAS __attribute__((address_space(3)))
; __global__ void __launch_bounds__(512, 2) mega_fwd(Params p) {
;     extern __shared__ __attribute__((aligned(16))) unsigned char lds_raw[];
;     LAS unsigned char* lds = (LAS unsigned char*)lds_raw;
;     cg::grid_group grid = cg::this_grid();
amdhsa.kernels:
  - .agpr_count:     0
    .args:
      - .offset:         0
        .size:           336
        .value_kind:     by_value
      - .offset:         336
        .size:           4
        .value_kind:     hidden_block_count_x
      - .offset:         340
        .size:           4
        .value_kind:     hidden_block_count_y
      - .offset:         344
        .size:           4
        .value_kind:     hidden_block_count_z
      - .offset:         348
        .size:           2
        .value_kind:     hidden_group_size_x
      - .offset:         350
        .size:           2
        .value_kind:     hidden_group_size_y
      - .offset:         352
        .size:           2
        .value_kind:     hidden_group_size_z
      - .offset:         354
        .size:           2
        .value_kind:     hidden_remainder_x
      - .offset:         356
        .size:           2
        .value_kind:     hidden_remainder_y
      - .offset:         358
        .size:           2
        .value_kind:     hidden_remainder_z
      - .offset:         376
        .size:           8
        .value_kind:     hidden_global_offset_x
      - .offset:         384
        .size:           8
        .value_kind:     hidden_global_offset_y
      - .offset:         392
        .size:           8
        .value_kind:     hidden_global_offset_z
      - .offset:         400
        .size:           2
        .value_kind:     hidden_grid_dims
      - .offset:         424
        .size:           8
        .value_kind:     hidden_multigrid_sync_arg
      - .offset:         456
        .size:           4
        .value_kind:     hidden_dynamic_lds_size
    .group_segment_fixed_size: 0
    .kernarg_segment_align: 8
    .kernarg_segment_size: 592
    .language:       OpenCL C
    .language_version:
      - 2
      - 0
    .max_flat_workgroup_size: 512
    .name:           _Z8mega_fwd6Params
    .private_segment_fixed_size: 0
    .sgpr_count:     108
    .sgpr_spill_count: 130
    .symbol:         _Z8mega_fwd6Params.kd
    .uniform_work_group_size: 1
    .uses_dynamic_stack: false
    .vgpr_count:     252
    .vgpr_spill_count: 0
    .wavefront_size: 64
